# v10 plus initial LDS fragment reads hoisted: QK reads above V staging, PV reads above the exp block
# baseline (speedup 1.0000x reference)
; #define SBAR() __builtin_amdgcn_sched_barrier(0)
; template <int DQK, int MODE, bool PIPE>
; DI void attn_core(const u16* __restrict__ Qg, const u16* __restrict__ Kg, const u16* __restrict__ Vtg, int ntiles,
;                   int kr_lo, int rs, int r_q, int c_q, int cs, const float* biasL, char* lds, f32x16 (&o)[4], float& l_out, int tid) {
;     ...
;   auto qk = [&](int t, f32x16& p0, f32x16& p1) {
;     const char* kb = lds + (t & 1) * A_BUF + r32 * KSTR + h * 16;
;     if (MODE != 0) {
; #pragma unroll
;       for (int i = 0; i < 16; ++i) { p0[i] = 0.f; p1[i] = 0.f; }
;     }
;     if (MODE == 0) {
;       constexpr int R = 4, NF = 2 * NKS;
;       const unsigned kaddr = (unsigned)(size_t)kb;
;       bf16x8 f[R];
;       SBAR();
;       f[0] = lds_rd128<0>(kaddr); f[1] = lds_rd128<32 * KSTR>(kaddr); f[2] = lds_rd128<32>(kaddr); f[3] = lds_rd128<32 * KSTR + 32>(kaddr);
;       SBAR();
;     ...
;   auto step = [&](int t, f32x16& c0, f32x16& c1, f32x16& n0, f32x16& n1) {
;     if (t + 1 < ntiles) swriteV((t + 1) & 1);
;     if (t + 2 < ntiles) gloadV(t + 2);
.LBB0_817:
	s_add_i32 s18, s6, 1
	s_bitcmp1_b32 s6, 0
	s_cselect_b32 s99, 0xa800, 0
	s_add_i32 s19, s99, 0
	v_add3_u32 v244, s19, v225, v0
	ds_read_b128 v[66:69], v244 offset:0
	ds_read_b128 v[82:85], v244 offset:0x3200
	ds_read_b128 v[228:231], v244 offset:32
	ds_read_b128 v[232:235], v244 offset:0x3220
	s_cmp_lt_u32 s18, s17
	s_cselect_b64 s[10:11], -1, 0
	s_cmp_ge_u32 s18, s17
	s_cbranch_scc1 .LBB0_819
	s_bitcmp1_b32 s18, 0
	s_cselect_b32 s7, 0xa800, 0
	v_add_u32_e32 v250, s7, v223
	v_add3_u32 v250, v250, v166, s33
	v_add_u32_e32 v251, s7, v224
	v_add3_u32 v251, v251, v166, s33
	s_waitcnt vmcnt(1)
	ds_write2_b64 v250, v[150:151], v[152:153] offset1:1
	s_waitcnt vmcnt(0)
	ds_write2_b64 v251, v[158:159], v[160:161] offset1:1

; #define MFMA(a, b, c) __builtin_amdgcn_mfma_f32_32x32x16_bf16((a), (b), (c), 0, 0, 0)
; DI int crow(int i, int h) { return (i & 3) + 8 * (i >> 2) + 4 * h; }
; #define SBAR() __builtin_amdgcn_sched_barrier(0)
; template <int DQK, int MODE, bool PIPE>
; DI void attn_core(const u16* __restrict__ Qg, const u16* __restrict__ Kg, const u16* __restrict__ Vtg, int ntiles,
;                   int kr_lo, int rs, int r_q, int c_q, int cs, const float* biasL, char* lds, f32x16 (&o)[4], float& l_out, int tid) {
;     ...
;       SBAR();
;       __builtin_amdgcn_s_setprio(1);
;       QkStep<DQK, 0, NF, R>::run(kaddr, f, qf, p0, p1, negm);
;       __builtin_amdgcn_s_setprio(0);
;     } else {
; #pragma unroll
;       for (int ks = 0; ks < NKS; ++ks) {
;         const bf16x8 k0 = *(const bf16x8*)(kb + ks * 32), k1 = *(const bf16x8*)(kb + 32 * KSTR + ks * 32);
;         p0 = MFMA(k0, qf[ks], p0); p1 = MFMA(k1, qf[ks], p1);
;       }
;     }
;     if (MODE == 1 && t >= 4) {
;       const int kr = kr_lo + t - 4;
;       const float* brow = biasL + (kr - r_q + 7) * 31 + 15 - c_q;
; #pragma unroll
;       for (int i = 0; i < 16; ++i) {
;         const int kc0 = crow(i, h), kc1 = 32 + kc0;
;         p0[i] = ((unsigned)(kc0 - cs) < 16u) ? p0[i] + brow[kc0] : -1e30f;
;         p1[i] = ((unsigned)(kc1 - cs) < 16u) ? p1[i] + brow[kc1] : -1e30f;
;         if ((i & 3) == 3) __builtin_amdgcn_sched_barrier(0);
;       }
;     }
;   };
;   auto sm_pv = [&](int t, f32x16& p0, f32x16& p1) {
;     asm volatile("s_nop 7\n\ts_nop 7\n\ts_nop 7" ::: "memory");
;     if (!NEGM && __any(m != 0.f)) {
; #pragma unroll
;       for (int i = 0; i < 16; ++i) {
;         asm("v_sub_f32 %0, %1, %2" : "=v"(p0[i]) : "v"(p0[i]), "v"(m));
;         asm("v_sub_f32 %0, %1, %2" : "=v"(p1[i]) : "v"(p1[i]), "v"(m));
;       }
;     }
.LBB0_821:
	s_setprio 1
	s_waitcnt lgkmcnt(2)
	v_mfma_f32_32x32x16_bf16 v[66:81], v[66:69], v[98:101], 0
	ds_read_b128 v[236:239], v244 offset:64
	v_mfma_f32_32x32x16_bf16 v[82:97], v[82:85], v[98:101], 0
	ds_read_b128 v[240:243], v244 offset:0x3240
	s_waitcnt lgkmcnt(2)
	v_mfma_f32_32x32x16_bf16 v[66:81], v[228:231], v[102:105], v[66:81]
	ds_read_b128 v[228:231], v244 offset:0x60
	v_mfma_f32_32x32x16_bf16 v[82:97], v[232:235], v[102:105], v[82:97]
	ds_read_b128 v[232:235], v244 offset:0x3260
	s_waitcnt lgkmcnt(2)
	v_mfma_f32_32x32x16_bf16 v[66:81], v[236:239], v[106:109], v[66:81]
	ds_read_b128 v[236:239], v244 offset:0x80
	v_mfma_f32_32x32x16_bf16 v[82:97], v[240:243], v[106:109], v[82:97]
	ds_read_b128 v[240:243], v244 offset:0x3280
	s_waitcnt lgkmcnt(2)
	v_mfma_f32_32x32x16_bf16 v[66:81], v[228:231], v[110:113], v[66:81]
	ds_read_b128 v[228:231], v244 offset:0xa0
	v_mfma_f32_32x32x16_bf16 v[82:97], v[232:235], v[110:113], v[82:97]
	ds_read_b128 v[232:235], v244 offset:0x32a0
	s_waitcnt lgkmcnt(2)
	v_mfma_f32_32x32x16_bf16 v[66:81], v[236:239], v[114:117], v[66:81]
	ds_read_b128 v[236:239], v244 offset:0xc0
	v_mfma_f32_32x32x16_bf16 v[82:97], v[240:243], v[114:117], v[82:97]
	ds_read_b128 v[240:243], v244 offset:0x32c0
	s_waitcnt lgkmcnt(2)
	v_mfma_f32_32x32x16_bf16 v[66:81], v[228:231], v[118:121], v[66:81]
	ds_read_b128 v[228:231], v244 offset:0xe0
	v_mfma_f32_32x32x16_bf16 v[82:97], v[232:235], v[118:121], v[82:97]
	ds_read_b128 v[232:235], v244 offset:0x32e0
	s_waitcnt lgkmcnt(2)
	v_mfma_f32_32x32x16_bf16 v[66:81], v[236:239], v[122:125], v[66:81]
	ds_read_b128 v[236:239], v244 offset:0x100
	v_mfma_f32_32x32x16_bf16 v[82:97], v[240:243], v[122:125], v[82:97]
	ds_read_b128 v[240:243], v244 offset:0x3300
	s_waitcnt lgkmcnt(2)
	v_mfma_f32_32x32x16_bf16 v[66:81], v[228:231], v[126:129], v[66:81]
	ds_read_b128 v[228:231], v244 offset:0x120
	v_mfma_f32_32x32x16_bf16 v[82:97], v[232:235], v[126:129], v[82:97]
	ds_read_b128 v[232:235], v244 offset:0x3320
	s_waitcnt lgkmcnt(2)
	v_mfma_f32_32x32x16_bf16 v[66:81], v[236:239], v[130:133], v[66:81]
	ds_read_b128 v[236:239], v244 offset:0x140
	v_mfma_f32_32x32x16_bf16 v[82:97], v[240:243], v[130:133], v[82:97]
	ds_read_b128 v[240:243], v244 offset:0x3340
	s_waitcnt lgkmcnt(2)
	v_mfma_f32_32x32x16_bf16 v[66:81], v[228:231], v[134:137], v[66:81]
	ds_read_b128 v[228:231], v244 offset:0x160
	v_mfma_f32_32x32x16_bf16 v[82:97], v[232:235], v[134:137], v[82:97]
	ds_read_b128 v[232:235], v244 offset:0x3360
	s_waitcnt lgkmcnt(2)
	v_mfma_f32_32x32x16_bf16 v[66:81], v[236:239], v[138:141], v[66:81]
	v_mfma_f32_32x32x16_bf16 v[82:97], v[240:243], v[138:141], v[82:97]
	s_waitcnt lgkmcnt(0)
	v_mfma_f32_32x32x16_bf16 v[66:81], v[228:231], v[142:145], v[66:81]
	v_mfma_f32_32x32x16_bf16 v[82:97], v[232:235], v[142:145], v[82:97]
	s_setprio 0
	s_nop 7
	s_nop 7
	v_cmp_neq_f32_e32 vcc, 0, v227
	s_cbranch_vccz .LBB0_823
	v_sub_f32 v66, v66, v227
	v_sub_f32 v82, v82, v227
	v_sub_f32 v67, v67, v227
	v_sub_f32 v83, v83, v227
	v_sub_f32 v68, v68, v227
	v_sub_f32 v84, v84, v227
	v_sub_f32 v69, v69, v227
	v_sub_f32 v85, v85, v227
	v_sub_f32 v70, v70, v227
	v_sub_f32 v86, v86, v227
	v_sub_f32 v71, v71, v227
	v_sub_f32 v87, v87, v227
	v_sub_f32 v72, v72, v227
	v_sub_f32 v88, v88, v227
	v_sub_f32 v73, v73, v227
	v_sub_f32 v89, v89, v227
	v_sub_f32 v74, v74, v227
	v_sub_f32 v90, v90, v227
	v_sub_f32 v75, v75, v227
	v_sub_f32 v91, v91, v227
	v_sub_f32 v76, v76, v227
	v_sub_f32 v92, v92, v227
	v_sub_f32 v77, v77, v227
	v_sub_f32 v93, v93, v227
	v_sub_f32 v78, v78, v227
	v_sub_f32 v94, v94, v227
	v_sub_f32 v79, v79, v227
	v_sub_f32 v95, v95, v227
	v_sub_f32 v80, v80, v227
	v_sub_f32 v96, v96, v227
	v_sub_f32 v81, v81, v227
	v_sub_f32 v97, v97, v227

; #define MFMA(a, b, c) __builtin_amdgcn_mfma_f32_32x32x16_bf16((a), (b), (c), 0, 0, 0)
; template <int N> DI void lgkm_wait() { asm volatile("s_waitcnt lgkmcnt(%0)" :: "i"(N) : "memory"); }
; #define SBAR() __builtin_amdgcn_sched_barrier(0)
;   static DI void run(unsigned vaddr, s16x4 (&lo)[R], s16x4 (&hi)[R], const f32x16& p0, const f32x16& p1, bf16x8& pfc, f32x16 (&o)[4]) {
;     constexpr int issued = (J + R < NF) ? (J + R) : NF;
;     if constexpr ((J & 3) == 0) {
;       if constexpr ((J >> 2) == 0) pfc = pack8<0>(p0);
;       else if constexpr ((J >> 2) == 1) pfc = pack8<8>(p0);
;       else if constexpr ((J >> 2) == 2) pfc = pack8<0>(p1);
;       else pfc = pack8<8>(p1);
;     }
;     lgkm_wait<2 * (issued - J - 1)>(); SBAR();
;     o[J & 3] = MFMA(__builtin_shufflevector(lo[J % R], hi[J % R], 0, 1, 2, 3, 4, 5, 6, 7), pfc, o[J & 3]);
;     SBAR();
;     if (J + R < NF) {
;       constexpr int off = ((J + R) & 3) * 32 * 136 + ((J + R) >> 2) * 32;
;       lo[J % R] = lds_rd64<off>(vaddr); hi[J % R] = lds_rd64<off + 16>(vaddr); SBAR();
;     }
;     if constexpr (J + 1 < NF) PvStep<J + 1, NF, R>::run(vaddr, lo, hi, p0, p1, pfc, o);
;   }
; template <int DQK, int MODE, bool PIPE>
; DI void attn_core(const u16* __restrict__ Qg, const u16* __restrict__ Kg, const u16* __restrict__ Vtg, int ntiles,
;                   int kr_lo, int rs, int r_q, int c_q, int cs, const float* biasL, char* lds, f32x16 (&o)[4], float& l_out, int tid) {
;     ...
;     for (int i = 0; i < 16; ++i) { p0[i] = __builtin_amdgcn_exp2f(p0[i]); p1[i] = __builtin_amdgcn_exp2f(p1[i]); ps += p0[i] + p1[i]; }
;     l += ps;
;     const char* vb = lds + (t & 1) * A_BUF + A_VOFF + r32 * 136 + h * 8;
;     {
;       bf16x8 pfc;
;       constexpr int R = PV_RING;
;       const unsigned vaddr = (unsigned)(size_t)vb;
;       s16x4 vlo[R], vhi[R];
;       SBAR();
;       vlo[0] = lds_rd64<0>(vaddr); vhi[0] = lds_rd64<16>(vaddr);
;       vlo[1] = lds_rd64<32 * 136>(vaddr); vhi[1] = lds_rd64<32 * 136 + 16>(vaddr);
;       if (R > 2) { vlo[2 % R] = lds_rd64<64 * 136>(vaddr); vhi[2 % R] = lds_rd64<64 * 136 + 16>(vaddr); }
;       if (R > 3) { vlo[3 % R] = lds_rd64<96 * 136>(vaddr); vhi[3 % R] = lds_rd64<96 * 136 + 16>(vaddr); }
;       SBAR();
;       __builtin_amdgcn_s_setprio(1);
;       PvStep<0, 16, R>::run(vaddr, vlo, vhi, p0, p1, pfc, o);
;       __builtin_amdgcn_s_setprio(0);
.LBB0_825:
	v_add_u32_e32 v228, s19, v226
	v_add3_u32 v248, v228, v168, s33
	ds_read_b64 v[228:229], v248 offset:0
	ds_read_b64 v[230:231], v248 offset:16
	ds_read_b64 v[232:233], v248 offset:0x1100
	ds_read_b64 v[234:235], v248 offset:0x1110
	ds_read_b64 v[236:237], v248 offset:0x2200
	ds_read_b64 v[238:239], v248 offset:0x2210
	ds_read_b64 v[240:241], v248 offset:0x3300
	ds_read_b64 v[242:243], v248 offset:0x3310
	v_exp_f32_e32 v66, v66
	v_exp_f32_e32 v82, v82
	v_exp_f32_e32 v67, v67
	v_exp_f32_e32 v83, v83
	v_exp_f32_e32 v68, v68
	v_exp_f32_e32 v84, v84
	v_exp_f32_e32 v69, v69
	v_exp_f32_e32 v85, v85
	v_exp_f32_e32 v70, v70
	v_exp_f32_e32 v86, v86
	v_exp_f32_e32 v71, v71
	v_exp_f32_e32 v87, v87
	v_exp_f32_e32 v72, v72
	v_exp_f32_e32 v88, v88
	v_exp_f32_e32 v73, v73
	v_exp_f32_e32 v89, v89
	v_exp_f32_e32 v74, v74
	v_exp_f32_e32 v90, v90
	v_exp_f32_e32 v75, v75
	v_exp_f32_e32 v91, v91
	v_exp_f32_e32 v76, v76
	v_exp_f32_e32 v92, v92
	v_exp_f32_e32 v77, v77
	v_exp_f32_e32 v93, v93
	v_exp_f32_e32 v78, v78
	v_exp_f32_e32 v94, v94
	v_exp_f32_e32 v79, v79
	v_exp_f32_e32 v95, v95
	v_exp_f32_e32 v80, v80
	v_exp_f32_e32 v96, v96
	v_exp_f32_e32 v81, v81
	v_exp_f32_e32 v97, v97
	s_setprio 1
	s_waitcnt lgkmcnt(4)
	v_cvt_pk_bf16_f32 v244, v66, v67
	v_cvt_pk_bf16_f32 v245, v68, v69
	v_cvt_pk_bf16_f32 v246, v70, v71
	v_cvt_pk_bf16_f32 v247, v72, v73
	s_nop 1
	v_mfma_f32_32x32x16_bf16 v[50:65], v[228:231], v[244:247], v[50:65]
	ds_read_b64 v[228:229], v248 offset:32
	ds_read_b64 v[230:231], v248 offset:48
	v_mfma_f32_32x32x16_bf16 v[34:49], v[232:235], v[244:247], v[34:49]
	ds_read_b64 v[232:233], v248 offset:0x1120
	ds_read_b64 v[234:235], v248 offset:0x1130
	s_waitcnt lgkmcnt(4)
	v_mfma_f32_32x32x16_bf16 v[18:33], v[236:239], v[244:247], v[18:33]
	ds_read_b64 v[236:237], v248 offset:0x2220
	ds_read_b64 v[238:239], v248 offset:0x2230
	v_mfma_f32_32x32x16_bf16 v[2:17], v[240:243], v[244:247], v[2:17]
	ds_read_b64 v[240:241], v248 offset:0x3320
	ds_read_b64 v[242:243], v248 offset:0x3330
	s_waitcnt lgkmcnt(4)
	v_cvt_pk_bf16_f32 v244, v74, v75
	v_cvt_pk_bf16_f32 v245, v76, v77
	v_cvt_pk_bf16_f32 v246, v78, v79
	v_cvt_pk_bf16_f32 v247, v80, v81
	s_nop 1
	v_mfma_f32_32x32x16_bf16 v[50:65], v[228:231], v[244:247], v[50:65]
	ds_read_b64 v[228:229], v248 offset:64
	ds_read_b64 v[230:231], v248 offset:0x50
	v_mfma_f32_32x32x16_bf16 v[34:49], v[232:235], v[244:247], v[34:49]
	ds_read_b64 v[232:233], v248 offset:0x1140
	ds_read_b64 v[234:235], v248 offset:0x1150
	s_waitcnt lgkmcnt(4)
	v_mfma_f32_32x32x16_bf16 v[18:33], v[236:239], v[244:247], v[18:33]
	ds_read_b64 v[236:237], v248 offset:0x2240
	ds_read_b64 v[238:239], v248 offset:0x2250
	v_mfma_f32_32x32x16_bf16 v[2:17], v[240:243], v[244:247], v[2:17]
	ds_read_b64 v[240:241], v248 offset:0x3340
	ds_read_b64 v[242:243], v248 offset:0x3350
	s_waitcnt lgkmcnt(4)
	v_cvt_pk_bf16_f32 v244, v82, v83
	v_cvt_pk_bf16_f32 v245, v84, v85
	v_cvt_pk_bf16_f32 v246, v86, v87
	v_cvt_pk_bf16_f32 v247, v88, v89
	s_nop 1
	v_mfma_f32_32x32x16_bf16 v[50:65], v[228:231], v[244:247], v[50:65]
	ds_read_b64 v[228:229], v248 offset:0x60
	ds_read_b64 v[230:231], v248 offset:0x70
	v_mfma_f32_32x32x16_bf16 v[34:49], v[232:235], v[244:247], v[34:49]
	ds_read_b64 v[232:233], v248 offset:0x1160
	ds_read_b64 v[234:235], v248 offset:0x1170
	s_waitcnt lgkmcnt(4)
	v_mfma_f32_32x32x16_bf16 v[18:33], v[236:239], v[244:247], v[18:33]
	ds_read_b64 v[236:237], v248 offset:0x2260
	ds_read_b64 v[238:239], v248 offset:0x2270
	v_mfma_f32_32x32x16_bf16 v[2:17], v[240:243], v[244:247], v[2:17]
	ds_read_b64 v[240:241], v248 offset:0x3360
	ds_read_b64 v[242:243], v248 offset:0x3370
	s_waitcnt lgkmcnt(4)
	v_cvt_pk_bf16_f32 v244, v90, v91
	v_cvt_pk_bf16_f32 v245, v92, v93
	v_cvt_pk_bf16_f32 v246, v94, v95
	v_cvt_pk_bf16_f32 v247, v96, v97
	s_nop 1
	v_mfma_f32_32x32x16_bf16 v[50:65], v[228:231], v[244:247], v[50:65]
	v_mfma_f32_32x32x16_bf16 v[34:49], v[232:235], v[244:247], v[34:49]
	s_waitcnt lgkmcnt(0)
	v_mfma_f32_32x32x16_bf16 v[18:33], v[236:239], v[244:247], v[18:33]
	v_mfma_f32_32x32x16_bf16 v[2:17], v[240:243], v[244:247], v[2:17]
	s_setprio 0
	s_andn2_b64 vcc, exec, s[10:11]
	s_cbranch_vccnz .LBB0_827
	s_bitcmp1_b32 s18, 0
	s_cselect_b32 s6, 0xa800, 0
	v_add3_u32 v228, s6, v167, v169
	v_add3_u32 v229, s6, v199, v217
	v_add3_u32 v230, s6, v220, v221
	s_waitcnt vmcnt(2)
	ds_write_b128 v228, v[146:149]
	s_waitcnt vmcnt(1)
	ds_write_b128 v229, v[154:157]
	s_waitcnt vmcnt(0)
	ds_write_b128 v230, v[162:165]

; template <int DQK, int MODE, bool PIPE>
; DI void attn_core(const u16* __restrict__ Qg, const u16* __restrict__ Kg, const u16* __restrict__ Vtg, int ntiles,
;                   int kr_lo, int rs, int r_q, int c_q, int cs, const float* biasL, char* lds, f32x16 (&o)[4], float& l_out, int tid) {
;     ...
;   auto qk = [&](int t, f32x16& p0, f32x16& p1) {
;     const char* kb = lds + (t & 1) * A_BUF + r32 * KSTR + h * 16;
;     if (MODE != 0) {
; #pragma unroll
;       for (int i = 0; i < 16; ++i) { p0[i] = 0.f; p1[i] = 0.f; }
;     }
;     if (MODE == 0) {
;       constexpr int R = 4, NF = 2 * NKS;
;       const unsigned kaddr = (unsigned)(size_t)kb;
;       bf16x8 f[R];
;       SBAR();
;       f[0] = lds_rd128<0>(kaddr); f[1] = lds_rd128<32 * KSTR>(kaddr); f[2] = lds_rd128<32>(kaddr); f[3] = lds_rd128<32 * KSTR + 32>(kaddr);
;       SBAR();
;       __builtin_amdgcn_s_setprio(1);
;       QkStep<DQK, 0, NF, R>::run(kaddr, f, qf, p0, p1, negm);
;       __builtin_amdgcn_s_setprio(0);
;     ...
;     float tmx;
;     {
;       float u[11];
; #pragma unroll
;       for (int i = 0; i < 5; ++i) {
;         asm("v_max3_f32 %0, %1, %2, %3" : "=v"(u[2 * i]) : "v"(p0[3 * i]), "v"(p0[3 * i + 1]), "v"(p0[3 * i + 2]));
;         asm("v_max3_f32 %0, %1, %2, %3" : "=v"(u[2 * i + 1]) : "v"(p1[3 * i]), "v"(p1[3 * i + 1]), "v"(p1[3 * i + 2]));
;       }
;       asm("v_max3_f32 %0, %1, %2, %3" : "=v"(u[10]) : "v"(p0[15]), "v"(p1[15]), "v"(u[0]));
;       float w0, w1, w2, w3;
;       asm("v_max3_f32 %0, %1, %2, %3" : "=v"(w0) : "v"(u[1]), "v"(u[2]), "v"(u[3]));
;       asm("v_max3_f32 %0, %1, %2, %3" : "=v"(w1) : "v"(u[4]), "v"(u[5]), "v"(u[6]));
;       asm("v_max3_f32 %0, %1, %2, %3" : "=v"(w2) : "v"(u[7]), "v"(u[8]), "v"(u[9]));
;       asm("v_max3_f32 %0, %1, %2, %3" : "=v"(w3) : "v"(u[10]), "v"(w0), "v"(w1));
;       asm("v_max_f32 %0, %1, %2" : "=v"(tmx) : "v"(w2), "v"(w3));
;     }
;     const bool t0 = (t == 0);
;     if (__any(tmx > THR || (t0 && tmx < -THR))) {
;       tmx = fmaxf(tmx, __shfl_xor(tmx, 32));
;       const float delta = t0 ? tmx : fmaxf(tmx, 0.f);
;       const float alpha = __builtin_amdgcn_exp2f(-fmaxf(delta, 0.f));
;       m += delta; l *= alpha;
; #pragma unroll
;       for (int d = 0; d < 4; ++d)
; #pragma unroll
;         for (int i = 0; i < 16; ++i) o[d][i] *= alpha;
; #pragma unroll
;       for (int i = 0; i < 16; ++i) { p0[i] -= delta; p1[i] -= delta; }
.LBB0_838:
	s_add_i32 s14, s15, 1
	s_add_i32 s16, s15, 2
	s_bitcmp1_b32 s15, 0
	s_cselect_b32 s15, 0xa800, 0
	v_add3_u32 v177, s15, v167, v0
	ds_read_b128 v[98:101], v177 offset:0
	ds_read_b128 v[216:219], v177 offset:0x1200
	ds_read_b128 v[220:223], v177 offset:32
	ds_read_b128 v[224:227], v177 offset:0x1220
	s_cmp_lt_u32 s14, s10
	s_cselect_b64 s[0:1], -1, 0
	s_cmp_ge_u32 s14, s10
	s_cbranch_scc1 .LBB0_840
	s_bitcmp1_b32 s14, 0
	s_cselect_b32 s6, 0xa800, 0
	v_add_u32_e32 v82, s6, v164
	v_add3_u32 v82, v82, v142, s33
	v_add_u32_e32 v83, s6, v165
	v_add3_u32 v83, v83, v142, s33
	s_waitcnt vmcnt(1)
	ds_write2_b64 v82, v[130:131], v[132:133] offset1:1
	s_waitcnt vmcnt(0)
	ds_write2_b64 v83, v[134:135], v[136:137] offset1:1
.LBB0_840:
	s_cmp_lt_u32 s16, s10
	s_cselect_b64 s[6:7], -1, 0
	s_cmp_ge_u32 s16, s10
	s_cbranch_scc1 .LBB0_842
	global_load_dwordx4 v[130:133], v[162:163], off
	global_load_dwordx4 v[134:137], v[150:151], off
.LBB0_842:
	s_setprio 1
	s_waitcnt lgkmcnt(2)
	v_mfma_f32_32x32x16_bf16 v[82:97], v[98:101], v[114:117], v[18:33]
	ds_read_b128 v[228:231], v177 offset:64
	v_mfma_f32_32x32x16_bf16 v[98:113], v[216:219], v[114:117], v[18:33]
	ds_read_b128 v[216:219], v177 offset:0x1240
	s_waitcnt lgkmcnt(2)
	v_mfma_f32_32x32x16_bf16 v[82:97], v[220:223], v[118:121], v[82:97]
	ds_read_b128 v[220:223], v177 offset:0x60
	v_mfma_f32_32x32x16_bf16 v[98:113], v[224:227], v[118:121], v[98:113]
	ds_read_b128 v[224:227], v177 offset:0x1260
	s_waitcnt lgkmcnt(2)
	v_mfma_f32_32x32x16_bf16 v[82:97], v[228:231], v[122:125], v[82:97]
	v_mfma_f32_32x32x16_bf16 v[98:113], v[216:219], v[122:125], v[98:113]
	s_waitcnt lgkmcnt(0)
	v_mfma_f32_32x32x16_bf16 v[82:97], v[220:223], v[126:129], v[82:97]
	v_mfma_f32_32x32x16_bf16 v[98:113], v[224:227], v[126:129], v[98:113]
	s_setprio 0
	v_max3_f32 v177, v82, v83, v84
	s_nop 7
	s_nop 7
	v_max3_f32 v199, v98, v99, v100
	v_max3_f32 v216, v85, v86, v87
	v_max3_f32 v217, v101, v102, v103
	v_max3_f32 v218, v88, v89, v90
	v_max3_f32 v177, v97, v113, v177
	v_max3_f32 v219, v104, v105, v106
	v_max3_f32 v220, v91, v92, v93
	v_max3_f32 v221, v107, v108, v109
	v_max3_f32 v199, v199, v216, v217
	v_max3_f32 v222, v94, v95, v96
	v_max3_f32 v223, v110, v111, v112
	v_max3_f32 v216, v218, v219, v220
	v_max3_f32 v217, v221, v222, v223
	v_max3_f32 v177, v177, v199, v216
	v_max_f32 v177, v217, v177
	v_cmp_lt_f32_e32 vcc, s66, v177
	s_cbranch_vccz .LBB0_844
	v_and_b32_e32 v19, 64, v189
	v_xor_b32_e32 v18, 32, v189
	v_add_u32_e32 v19, 64, v19
	v_cmp_lt_i32_e32 vcc, v18, v19
	s_nop 1
	v_cndmask_b32_e32 v18, v189, v18, vcc
	v_lshlrev_b32_e32 v18, 2, v18
	ds_bpermute_b32 v18, v18, v177
	s_waitcnt lgkmcnt(0)
	v_max3_f32 v18, v177, v18, 0
	v_exp_f32_e64 v20, -v18
	v_add_f32_e32 v175, v175, v18
	v_pk_add_f32 v[82:83], v[82:83], v[18:19] op_sel_hi:[1,0] neg_lo:[0,1] neg_hi:[0,1]
	v_pk_add_f32 v[98:99], v[98:99], v[18:19] op_sel_hi:[1,0] neg_lo:[0,1] neg_hi:[0,1]
	v_pk_add_f32 v[84:85], v[84:85], v[18:19] op_sel_hi:[1,0] neg_lo:[0,1] neg_hi:[0,1]
	v_pk_add_f32 v[100:101], v[100:101], v[18:19] op_sel_hi:[1,0] neg_lo:[0,1] neg_hi:[0,1]
	v_pk_add_f32 v[86:87], v[86:87], v[18:19] op_sel_hi:[1,0] neg_lo:[0,1] neg_hi:[0,1]
	v_pk_add_f32 v[102:103], v[102:103], v[18:19] op_sel_hi:[1,0] neg_lo:[0,1] neg_hi:[0,1]
	v_pk_add_f32 v[88:89], v[88:89], v[18:19] op_sel_hi:[1,0] neg_lo:[0,1] neg_hi:[0,1]
	v_pk_add_f32 v[104:105], v[104:105], v[18:19] op_sel_hi:[1,0] neg_lo:[0,1] neg_hi:[0,1]
	v_pk_add_f32 v[90:91], v[90:91], v[18:19] op_sel_hi:[1,0] neg_lo:[0,1] neg_hi:[0,1]
	v_pk_add_f32 v[106:107], v[106:107], v[18:19] op_sel_hi:[1,0] neg_lo:[0,1] neg_hi:[0,1]
	v_pk_add_f32 v[92:93], v[92:93], v[18:19] op_sel_hi:[1,0] neg_lo:[0,1] neg_hi:[0,1]
	v_pk_add_f32 v[108:109], v[108:109], v[18:19] op_sel_hi:[1,0] neg_lo:[0,1] neg_hi:[0,1]
	v_pk_add_f32 v[94:95], v[94:95], v[18:19] op_sel_hi:[1,0] neg_lo:[0,1] neg_hi:[0,1]
	v_pk_add_f32 v[110:111], v[110:111], v[18:19] op_sel_hi:[1,0] neg_lo:[0,1] neg_hi:[0,1]
	v_pk_add_f32 v[96:97], v[96:97], v[18:19] op_sel_hi:[1,0] neg_lo:[0,1] neg_hi:[0,1]
	v_pk_add_f32 v[112:113], v[112:113], v[18:19] op_sel_hi:[1,0] neg_lo:[0,1] neg_hi:[0,1]
	v_xor_b32_e32 v18, 0x80000000, v175
	v_mul_f32_e32 v176, v176, v20
	v_pk_mul_f32 v[80:81], v[80:81], v[20:21] op_sel_hi:[1,0]
	v_pk_mul_f32 v[78:79], v[78:79], v[20:21] op_sel_hi:[1,0]
	v_pk_mul_f32 v[76:77], v[76:77], v[20:21] op_sel_hi:[1,0]
	v_pk_mul_f32 v[74:75], v[74:75], v[20:21] op_sel_hi:[1,0]
	v_pk_mul_f32 v[72:73], v[72:73], v[20:21] op_sel_hi:[1,0]
	v_pk_mul_f32 v[70:71], v[70:71], v[20:21] op_sel_hi:[1,0]
	v_pk_mul_f32 v[68:69], v[68:69], v[20:21] op_sel_hi:[1,0]
	v_pk_mul_f32 v[66:67], v[66:67], v[20:21] op_sel_hi:[1,0]
	v_pk_mul_f32 v[64:65], v[64:65], v[20:21] op_sel_hi:[1,0]
	v_pk_mul_f32 v[62:63], v[62:63], v[20:21] op_sel_hi:[1,0]
	v_pk_mul_f32 v[60:61], v[60:61], v[20:21] op_sel_hi:[1,0]
	v_pk_mul_f32 v[58:59], v[58:59], v[20:21] op_sel_hi:[1,0]
	v_pk_mul_f32 v[56:57], v[56:57], v[20:21] op_sel_hi:[1,0]
	v_pk_mul_f32 v[54:55], v[54:55], v[20:21] op_sel_hi:[1,0]
	v_pk_mul_f32 v[52:53], v[52:53], v[20:21] op_sel_hi:[1,0]
	v_pk_mul_f32 v[50:51], v[50:51], v[20:21] op_sel_hi:[1,0]
	v_pk_mul_f32 v[48:49], v[48:49], v[20:21] op_sel_hi:[1,0]
	v_pk_mul_f32 v[46:47], v[46:47], v[20:21] op_sel_hi:[1,0]
	v_pk_mul_f32 v[44:45], v[44:45], v[20:21] op_sel_hi:[1,0]
	v_pk_mul_f32 v[42:43], v[42:43], v[20:21] op_sel_hi:[1,0]
	v_pk_mul_f32 v[40:41], v[40:41], v[20:21] op_sel_hi:[1,0]
	v_pk_mul_f32 v[38:39], v[38:39], v[20:21] op_sel_hi:[1,0]
	v_pk_mul_f32 v[36:37], v[36:37], v[20:21] op_sel_hi:[1,0]
	v_pk_mul_f32 v[34:35], v[34:35], v[20:21] op_sel_hi:[1,0]
	v_pk_mul_f32 v[16:17], v[16:17], v[20:21] op_sel_hi:[1,0]
	v_pk_mul_f32 v[14:15], v[14:15], v[20:21] op_sel_hi:[1,0]
	v_pk_mul_f32 v[12:13], v[12:13], v[20:21] op_sel_hi:[1,0]
	v_pk_mul_f32 v[10:11], v[10:11], v[20:21] op_sel_hi:[1,0]
	v_pk_mul_f32 v[8:9], v[8:9], v[20:21] op_sel_hi:[1,0]
	v_pk_mul_f32 v[6:7], v[6:7], v[20:21] op_sel_hi:[1,0]
	v_pk_mul_f32 v[4:5], v[4:5], v[20:21] op_sel_hi:[1,0]
	v_pk_mul_f32 v[2:3], v[2:3], v[20:21] op_sel_hi:[1,0]
	v_mov_b32_e32 v19, v18
	v_mov_b32_e32 v20, v18
	v_mov_b32_e32 v21, v18
	v_mov_b32_e32 v22, v18
	v_mov_b32_e32 v23, v18
	v_mov_b32_e32 v24, v18
	v_mov_b32_e32 v25, v18
	v_mov_b32_e32 v26, v18
	v_mov_b32_e32 v27, v18
	v_mov_b32_e32 v28, v18
	v_mov_b32_e32 v29, v18
	v_mov_b32_e32 v30, v18
	v_mov_b32_e32 v31, v18
	v_mov_b32_e32 v32, v18
	v_mov_b32_e32 v33, v18
; #define MFMA(a, b, c) __builtin_amdgcn_mfma_f32_32x32x16_bf16((a), (b), (c), 0, 0, 0)
; template <int N> DI void lgkm_wait() { asm volatile("s_waitcnt lgkmcnt(%0)" :: "i"(N) : "memory"); }
; #define SBAR() __builtin_amdgcn_sched_barrier(0)
;   static DI void run(unsigned vaddr, s16x4 (&lo)[R], s16x4 (&hi)[R], const f32x16& p0, const f32x16& p1, bf16x8& pfc, f32x16 (&o)[4]) {
;     constexpr int issued = (J + R < NF) ? (J + R) : NF;
;     if constexpr ((J & 3) == 0) {
;       if constexpr ((J >> 2) == 0) pfc = pack8<0>(p0);
;       else if constexpr ((J >> 2) == 1) pfc = pack8<8>(p0);
;       else if constexpr ((J >> 2) == 2) pfc = pack8<0>(p1);
;       else pfc = pack8<8>(p1);
;     }
;     lgkm_wait<2 * (issued - J - 1)>(); SBAR();
;     o[J & 3] = MFMA(__builtin_shufflevector(lo[J % R], hi[J % R], 0, 1, 2, 3, 4, 5, 6, 7), pfc, o[J & 3]);
;     SBAR();
;     if (J + R < NF) {
;       constexpr int off = ((J + R) & 3) * 32 * 136 + ((J + R) >> 2) * 32;
;       lo[J % R] = lds_rd64<off>(vaddr); hi[J % R] = lds_rd64<off + 16>(vaddr); SBAR();
;     }
;     if constexpr (J + 1 < NF) PvStep<J + 1, NF, R>::run(vaddr, lo, hi, p0, p1, pfc, o);
;   }
; template <int DQK, int MODE, bool PIPE>
; DI void attn_core(const u16* __restrict__ Qg, const u16* __restrict__ Kg, const u16* __restrict__ Vtg, int ntiles,
;                   int kr_lo, int rs, int r_q, int c_q, int cs, const float* biasL, char* lds, f32x16 (&o)[4], float& l_out, int tid) {
;     ...
;     for (int i = 0; i < 16; ++i) { p0[i] = __builtin_amdgcn_exp2f(p0[i]); p1[i] = __builtin_amdgcn_exp2f(p1[i]); ps += p0[i] + p1[i]; }
;     l += ps;
;     const char* vb = lds + (t & 1) * A_BUF + A_VOFF + r32 * 136 + h * 8;
;     {
;       bf16x8 pfc;
;       constexpr int R = PV_RING;
;       const unsigned vaddr = (unsigned)(size_t)vb;
;       s16x4 vlo[R], vhi[R];
;       SBAR();
;       vlo[0] = lds_rd64<0>(vaddr); vhi[0] = lds_rd64<16>(vaddr);
;       vlo[1] = lds_rd64<32 * 136>(vaddr); vhi[1] = lds_rd64<32 * 136 + 16>(vaddr);
;       if (R > 2) { vlo[2 % R] = lds_rd64<64 * 136>(vaddr); vhi[2 % R] = lds_rd64<64 * 136 + 16>(vaddr); }
;       if (R > 3) { vlo[3 % R] = lds_rd64<96 * 136>(vaddr); vhi[3 % R] = lds_rd64<96 * 136 + 16>(vaddr); }
;       SBAR();
;       __builtin_amdgcn_s_setprio(1);
;       PvStep<0, 16, R>::run(vaddr, vlo, vhi, p0, p1, pfc, o);
;       __builtin_amdgcn_s_setprio(0);
.LBB0_844:
	v_add_u32_e32 v177, s15, v168
	v_add3_u32 v177, v177, v166, s33
	ds_read_b64 v[216:217], v177 offset:0
	ds_read_b64 v[218:219], v177 offset:16
	ds_read_b64 v[220:221], v177 offset:0x1100
	ds_read_b64 v[222:223], v177 offset:0x1110
	ds_read_b64 v[224:225], v177 offset:0x2200
	ds_read_b64 v[226:227], v177 offset:0x2210
	ds_read_b64 v[228:229], v177 offset:0x3300
	ds_read_b64 v[230:231], v177 offset:0x3310
	v_exp_f32_e32 v82, v82
	v_exp_f32_e32 v98, v98
	v_exp_f32_e32 v83, v83
	v_exp_f32_e32 v99, v99
	v_exp_f32_e32 v84, v84
	v_exp_f32_e32 v100, v100
	v_exp_f32_e32 v85, v85
	v_exp_f32_e32 v101, v101
	v_exp_f32_e32 v86, v86
	v_exp_f32_e32 v102, v102
	v_exp_f32_e32 v87, v87
	v_exp_f32_e32 v103, v103
	v_exp_f32_e32 v88, v88
	v_exp_f32_e32 v104, v104
	v_exp_f32_e32 v89, v89
	v_exp_f32_e32 v105, v105
	v_exp_f32_e32 v90, v90
	v_exp_f32_e32 v106, v106
	v_exp_f32_e32 v91, v91
	v_exp_f32_e32 v107, v107
	v_exp_f32_e32 v92, v92
	v_exp_f32_e32 v108, v108
	v_exp_f32_e32 v93, v93
	v_exp_f32_e32 v109, v109
	v_exp_f32_e32 v94, v94
	v_exp_f32_e32 v110, v110
	v_exp_f32_e32 v95, v95
	v_exp_f32_e32 v111, v111
	v_exp_f32_e32 v96, v96
	v_exp_f32_e32 v112, v112
	v_exp_f32_e32 v97, v97
	v_exp_f32_e32 v113, v113
	s_setprio 1
	s_waitcnt lgkmcnt(4)
	v_cvt_pk_bf16_f32 v232, v82, v83
	v_cvt_pk_bf16_f32 v233, v84, v85
	v_cvt_pk_bf16_f32 v234, v86, v87
	v_cvt_pk_bf16_f32 v235, v88, v89
	s_nop 1
	v_mfma_f32_32x32x16_bf16 v[66:81], v[216:219], v[232:235], v[66:81]
	ds_read_b64 v[216:217], v177 offset:32
	ds_read_b64 v[218:219], v177 offset:48
	v_mfma_f32_32x32x16_bf16 v[50:65], v[220:223], v[232:235], v[50:65]
	ds_read_b64 v[220:221], v177 offset:0x1120
	ds_read_b64 v[222:223], v177 offset:0x1130
	s_waitcnt lgkmcnt(4)
	v_mfma_f32_32x32x16_bf16 v[34:49], v[224:227], v[232:235], v[34:49]
	ds_read_b64 v[224:225], v177 offset:0x2220
	ds_read_b64 v[226:227], v177 offset:0x2230
	v_mfma_f32_32x32x16_bf16 v[2:17], v[228:231], v[232:235], v[2:17]
	ds_read_b64 v[228:229], v177 offset:0x3320
	ds_read_b64 v[230:231], v177 offset:0x3330
	s_waitcnt lgkmcnt(4)
	v_cvt_pk_bf16_f32 v232, v90, v91
	v_cvt_pk_bf16_f32 v233, v92, v93
	v_cvt_pk_bf16_f32 v234, v94, v95
	v_cvt_pk_bf16_f32 v235, v96, v97
	s_nop 1
	v_mfma_f32_32x32x16_bf16 v[66:81], v[216:219], v[232:235], v[66:81]
	ds_read_b64 v[216:217], v177 offset:64
	ds_read_b64 v[218:219], v177 offset:0x50
	v_mfma_f32_32x32x16_bf16 v[50:65], v[220:223], v[232:235], v[50:65]
	ds_read_b64 v[220:221], v177 offset:0x1140
	ds_read_b64 v[222:223], v177 offset:0x1150
	s_waitcnt lgkmcnt(4)
	v_mfma_f32_32x32x16_bf16 v[34:49], v[224:227], v[232:235], v[34:49]
	ds_read_b64 v[224:225], v177 offset:0x2240
	ds_read_b64 v[226:227], v177 offset:0x2250
	v_mfma_f32_32x32x16_bf16 v[2:17], v[228:231], v[232:235], v[2:17]
	ds_read_b64 v[228:229], v177 offset:0x3340
	ds_read_b64 v[230:231], v177 offset:0x3350
	s_waitcnt lgkmcnt(4)
	v_cvt_pk_bf16_f32 v232, v98, v99
	v_cvt_pk_bf16_f32 v233, v100, v101
	v_cvt_pk_bf16_f32 v234, v102, v103
	v_cvt_pk_bf16_f32 v235, v104, v105
	s_nop 1
	v_mfma_f32_32x32x16_bf16 v[66:81], v[216:219], v[232:235], v[66:81]
	ds_read_b64 v[216:217], v177 offset:0x60
	ds_read_b64 v[218:219], v177 offset:0x70
	v_mfma_f32_32x32x16_bf16 v[50:65], v[220:223], v[232:235], v[50:65]
	ds_read_b64 v[220:221], v177 offset:0x1160
	ds_read_b64 v[222:223], v177 offset:0x1170
	s_waitcnt lgkmcnt(4)
	v_mfma_f32_32x32x16_bf16 v[34:49], v[224:227], v[232:235], v[34:49]
	ds_read_b64 v[224:225], v177 offset:0x2260
	ds_read_b64 v[226:227], v177 offset:0x2270
	v_mfma_f32_32x32x16_bf16 v[2:17], v[228:231], v[232:235], v[2:17]
	ds_read_b64 v[228:229], v177 offset:0x3360
	ds_read_b64 v[230:231], v177 offset:0x3370
	s_waitcnt lgkmcnt(4)
	v_cvt_pk_bf16_f32 v232, v106, v107
	v_cvt_pk_bf16_f32 v233, v108, v109
	v_cvt_pk_bf16_f32 v234, v110, v111
	v_cvt_pk_bf16_f32 v235, v112, v113
	s_nop 1
	v_mfma_f32_32x32x16_bf16 v[66:81], v[216:219], v[232:235], v[66:81]
	v_mfma_f32_32x32x16_bf16 v[50:65], v[220:223], v[232:235], v[50:65]
	s_waitcnt lgkmcnt(0)
	v_mfma_f32_32x32x16_bf16 v[34:49], v[224:227], v[232:235], v[34:49]
	v_mfma_f32_32x32x16_bf16 v[2:17], v[228:231], v[232:235], v[2:17]
	s_setprio 0
	s_andn2_b64 vcc, exec, s[0:1]
	s_cbranch_vccnz .LBB0_846
	s_bitcmp1_b32 s14, 0
	s_cselect_b32 s0, 0xa800, 0
	v_add_u32_e32 v177, s0, v143
	s_waitcnt vmcnt(0)
	ds_write_b128 v177, v[138:141]

; template <int DQK, int MODE, bool PIPE>
; DI void attn_core(const u16* __restrict__ Qg, const u16* __restrict__ Kg, const u16* __restrict__ Vtg, int ntiles,
;                   int kr_lo, int rs, int r_q, int c_q, int cs, const float* biasL, char* lds, f32x16 (&o)[4], float& l_out, int tid) {
;     ...
;   auto qk = [&](int t, f32x16& p0, f32x16& p1) {
;     const char* kb = lds + (t & 1) * A_BUF + r32 * KSTR + h * 16;
;     if (MODE != 0) {
; #pragma unroll
;       for (int i = 0; i < 16; ++i) { p0[i] = 0.f; p1[i] = 0.f; }
;     }
;     if (MODE == 0) {
;       constexpr int R = 4, NF = 2 * NKS;
;       const unsigned kaddr = (unsigned)(size_t)kb;
;       bf16x8 f[R];
;       SBAR();
;       f[0] = lds_rd128<0>(kaddr); f[1] = lds_rd128<32 * KSTR>(kaddr); f[2] = lds_rd128<32>(kaddr); f[3] = lds_rd128<32 * KSTR + 32>(kaddr);
;       SBAR();
;       __builtin_amdgcn_s_setprio(1);
;       QkStep<DQK, 0, NF, R>::run(kaddr, f, qf, p0, p1, negm);
;       __builtin_amdgcn_s_setprio(0);
;     ...
;     float tmx;
;     {
;       float u[11];
; #pragma unroll
;       for (int i = 0; i < 5; ++i) {
;         asm("v_max3_f32 %0, %1, %2, %3" : "=v"(u[2 * i]) : "v"(p0[3 * i]), "v"(p0[3 * i + 1]), "v"(p0[3 * i + 2]));
;         asm("v_max3_f32 %0, %1, %2, %3" : "=v"(u[2 * i + 1]) : "v"(p1[3 * i]), "v"(p1[3 * i + 1]), "v"(p1[3 * i + 2]));
;       }
;       asm("v_max3_f32 %0, %1, %2, %3" : "=v"(u[10]) : "v"(p0[15]), "v"(p1[15]), "v"(u[0]));
;       float w0, w1, w2, w3;
;       asm("v_max3_f32 %0, %1, %2, %3" : "=v"(w0) : "v"(u[1]), "v"(u[2]), "v"(u[3]));
;       asm("v_max3_f32 %0, %1, %2, %3" : "=v"(w1) : "v"(u[4]), "v"(u[5]), "v"(u[6]));
;       asm("v_max3_f32 %0, %1, %2, %3" : "=v"(w2) : "v"(u[7]), "v"(u[8]), "v"(u[9]));
;       asm("v_max3_f32 %0, %1, %2, %3" : "=v"(w3) : "v"(u[10]), "v"(w0), "v"(w1));
;       asm("v_max_f32 %0, %1, %2" : "=v"(tmx) : "v"(w2), "v"(w3));
;     }
;     const bool t0 = (t == 0);
;     if (__any(tmx > THR || (t0 && tmx < -THR))) {
;       tmx = fmaxf(tmx, __shfl_xor(tmx, 32));
;       const float delta = t0 ? tmx : fmaxf(tmx, 0.f);
;       const float alpha = __builtin_amdgcn_exp2f(-fmaxf(delta, 0.f));
;       m += delta; l *= alpha;
; #pragma unroll
;       for (int d = 0; d < 4; ++d)
; #pragma unroll
;         for (int i = 0; i < 16; ++i) o[d][i] *= alpha;
; #pragma unroll
;       for (int i = 0; i < 16; ++i) { p0[i] -= delta; p1[i] -= delta; }
.LBB0_854:
	s_add_i32 s11, s12, 1
	s_add_i32 s14, s12, 2
	s_bitcmp1_b32 s12, 0
	s_cselect_b32 s12, 0xa800, 0
	v_add3_u32 v160, s12, v167, v0
	ds_read_b128 v[98:101], v160 offset:0
	ds_read_b128 v[156:159], v160 offset:0x1200
	ds_read_b128 v[170:173], v160 offset:32
	ds_read_b128 v[174:177], v160 offset:0x1220
	s_cmp_lt_u32 s11, s10
	s_cselect_b64 s[0:1], -1, 0
	s_cmp_ge_u32 s11, s10
	s_cbranch_scc1 .LBB0_856
	s_bitcmp1_b32 s11, 0
	s_cselect_b32 s6, 0xa800, 0
	v_add_u32_e32 v82, s6, v164
	v_add3_u32 v82, v82, v142, s33
	v_add_u32_e32 v83, s6, v165
	v_add3_u32 v83, v83, v142, s33
	s_waitcnt vmcnt(1)
	ds_write2_b64 v82, v[130:131], v[132:133] offset1:1
	s_waitcnt vmcnt(0)
	ds_write2_b64 v83, v[134:135], v[136:137] offset1:1
.LBB0_856:
	s_cmp_lt_u32 s14, s10
	s_cselect_b64 s[6:7], -1, 0
	s_cmp_ge_u32 s14, s10
	s_cbranch_scc1 .LBB0_858
	global_load_dwordx4 v[130:133], v[146:147], off
	global_load_dwordx4 v[134:137], v[148:149], off
.LBB0_858:
	s_setprio 1
	s_waitcnt lgkmcnt(2)
	v_mfma_f32_32x32x16_bf16 v[82:97], v[98:101], v[114:117], v[34:49]
	ds_read_b128 v[216:219], v160 offset:64
	v_mfma_f32_32x32x16_bf16 v[98:113], v[156:159], v[114:117], v[34:49]
	ds_read_b128 v[156:159], v160 offset:0x1240
	s_waitcnt lgkmcnt(2)
	v_mfma_f32_32x32x16_bf16 v[82:97], v[170:173], v[118:121], v[82:97]
	ds_read_b128 v[170:173], v160 offset:0x60
	v_mfma_f32_32x32x16_bf16 v[98:113], v[174:177], v[118:121], v[98:113]
	ds_read_b128 v[174:177], v160 offset:0x1260
	s_waitcnt lgkmcnt(2)
	v_mfma_f32_32x32x16_bf16 v[82:97], v[216:219], v[122:125], v[82:97]
	v_mfma_f32_32x32x16_bf16 v[98:113], v[156:159], v[122:125], v[98:113]
	s_waitcnt lgkmcnt(0)
	v_mfma_f32_32x32x16_bf16 v[82:97], v[170:173], v[126:129], v[82:97]
	v_mfma_f32_32x32x16_bf16 v[98:113], v[174:177], v[126:129], v[98:113]
	s_setprio 0
	v_max3_f32 v156, v82, v83, v84
	s_nop 7
	s_nop 7
	v_max3_f32 v157, v98, v99, v100
	v_max3_f32 v158, v85, v86, v87
	v_max3_f32 v159, v101, v102, v103
	v_max3_f32 v160, v88, v89, v90
	v_max3_f32 v156, v97, v113, v156
	v_max3_f32 v161, v104, v105, v106
	v_max3_f32 v163, v91, v92, v93
	v_max3_f32 v169, v107, v108, v109
	v_max3_f32 v157, v157, v158, v159
	v_max3_f32 v170, v94, v95, v96
	v_max3_f32 v171, v110, v111, v112
	v_max3_f32 v158, v160, v161, v163
	v_max3_f32 v159, v169, v170, v171
	v_max3_f32 v156, v156, v157, v158
	v_max_f32 v156, v159, v156
	v_cmp_lt_f32_e32 vcc, s66, v156
	s_cbranch_vccz .LBB0_860
	ds_bpermute_b32 v34, v162, v156
	s_waitcnt lgkmcnt(0)
	v_max3_f32 v34, v156, v34, 0
	v_exp_f32_e64 v36, -v34
	v_add_f32_e32 v154, v154, v34
	v_pk_add_f32 v[82:83], v[82:83], v[34:35] op_sel_hi:[1,0] neg_lo:[0,1] neg_hi:[0,1]
	v_pk_add_f32 v[98:99], v[98:99], v[34:35] op_sel_hi:[1,0] neg_lo:[0,1] neg_hi:[0,1]
	v_pk_add_f32 v[84:85], v[84:85], v[34:35] op_sel_hi:[1,0] neg_lo:[0,1] neg_hi:[0,1]
	v_pk_add_f32 v[100:101], v[100:101], v[34:35] op_sel_hi:[1,0] neg_lo:[0,1] neg_hi:[0,1]
	v_pk_add_f32 v[86:87], v[86:87], v[34:35] op_sel_hi:[1,0] neg_lo:[0,1] neg_hi:[0,1]
	v_pk_add_f32 v[102:103], v[102:103], v[34:35] op_sel_hi:[1,0] neg_lo:[0,1] neg_hi:[0,1]
	v_pk_add_f32 v[88:89], v[88:89], v[34:35] op_sel_hi:[1,0] neg_lo:[0,1] neg_hi:[0,1]
	v_pk_add_f32 v[104:105], v[104:105], v[34:35] op_sel_hi:[1,0] neg_lo:[0,1] neg_hi:[0,1]
	v_pk_add_f32 v[90:91], v[90:91], v[34:35] op_sel_hi:[1,0] neg_lo:[0,1] neg_hi:[0,1]
	v_pk_add_f32 v[106:107], v[106:107], v[34:35] op_sel_hi:[1,0] neg_lo:[0,1] neg_hi:[0,1]
	v_pk_add_f32 v[92:93], v[92:93], v[34:35] op_sel_hi:[1,0] neg_lo:[0,1] neg_hi:[0,1]
	v_pk_add_f32 v[108:109], v[108:109], v[34:35] op_sel_hi:[1,0] neg_lo:[0,1] neg_hi:[0,1]
	v_pk_add_f32 v[94:95], v[94:95], v[34:35] op_sel_hi:[1,0] neg_lo:[0,1] neg_hi:[0,1]
	v_pk_add_f32 v[110:111], v[110:111], v[34:35] op_sel_hi:[1,0] neg_lo:[0,1] neg_hi:[0,1]
	v_pk_add_f32 v[96:97], v[96:97], v[34:35] op_sel_hi:[1,0] neg_lo:[0,1] neg_hi:[0,1]
	v_pk_add_f32 v[112:113], v[112:113], v[34:35] op_sel_hi:[1,0] neg_lo:[0,1] neg_hi:[0,1]
	v_xor_b32_e32 v34, 0x80000000, v154
	v_mul_f32_e32 v155, v155, v36
	v_pk_mul_f32 v[80:81], v[80:81], v[36:37] op_sel_hi:[1,0]
	v_pk_mul_f32 v[78:79], v[78:79], v[36:37] op_sel_hi:[1,0]
	v_pk_mul_f32 v[76:77], v[76:77], v[36:37] op_sel_hi:[1,0]
	v_pk_mul_f32 v[74:75], v[74:75], v[36:37] op_sel_hi:[1,0]
	v_pk_mul_f32 v[72:73], v[72:73], v[36:37] op_sel_hi:[1,0]
	v_pk_mul_f32 v[70:71], v[70:71], v[36:37] op_sel_hi:[1,0]
	v_pk_mul_f32 v[68:69], v[68:69], v[36:37] op_sel_hi:[1,0]
	v_pk_mul_f32 v[66:67], v[66:67], v[36:37] op_sel_hi:[1,0]
	v_pk_mul_f32 v[64:65], v[64:65], v[36:37] op_sel_hi:[1,0]
	v_pk_mul_f32 v[62:63], v[62:63], v[36:37] op_sel_hi:[1,0]
	v_pk_mul_f32 v[60:61], v[60:61], v[36:37] op_sel_hi:[1,0]
	v_pk_mul_f32 v[58:59], v[58:59], v[36:37] op_sel_hi:[1,0]
	v_pk_mul_f32 v[56:57], v[56:57], v[36:37] op_sel_hi:[1,0]
	v_pk_mul_f32 v[54:55], v[54:55], v[36:37] op_sel_hi:[1,0]
	v_pk_mul_f32 v[52:53], v[52:53], v[36:37] op_sel_hi:[1,0]
	v_pk_mul_f32 v[50:51], v[50:51], v[36:37] op_sel_hi:[1,0]
	v_pk_mul_f32 v[32:33], v[32:33], v[36:37] op_sel_hi:[1,0]
	v_pk_mul_f32 v[30:31], v[30:31], v[36:37] op_sel_hi:[1,0]
	v_pk_mul_f32 v[28:29], v[28:29], v[36:37] op_sel_hi:[1,0]
	v_pk_mul_f32 v[26:27], v[26:27], v[36:37] op_sel_hi:[1,0]
	v_pk_mul_f32 v[24:25], v[24:25], v[36:37] op_sel_hi:[1,0]
	v_pk_mul_f32 v[22:23], v[22:23], v[36:37] op_sel_hi:[1,0]
	v_pk_mul_f32 v[20:21], v[20:21], v[36:37] op_sel_hi:[1,0]
	v_pk_mul_f32 v[18:19], v[18:19], v[36:37] op_sel_hi:[1,0]
	v_pk_mul_f32 v[16:17], v[16:17], v[36:37] op_sel_hi:[1,0]
	v_pk_mul_f32 v[14:15], v[14:15], v[36:37] op_sel_hi:[1,0]
	v_pk_mul_f32 v[12:13], v[12:13], v[36:37] op_sel_hi:[1,0]
	v_pk_mul_f32 v[10:11], v[10:11], v[36:37] op_sel_hi:[1,0]
	v_pk_mul_f32 v[8:9], v[8:9], v[36:37] op_sel_hi:[1,0]
	v_pk_mul_f32 v[6:7], v[6:7], v[36:37] op_sel_hi:[1,0]
	v_pk_mul_f32 v[4:5], v[4:5], v[36:37] op_sel_hi:[1,0]
	v_pk_mul_f32 v[2:3], v[2:3], v[36:37] op_sel_hi:[1,0]
	v_mov_b32_e32 v35, v34
	v_mov_b32_e32 v36, v34
	v_mov_b32_e32 v37, v34
	v_mov_b32_e32 v38, v34
	v_mov_b32_e32 v39, v34
	v_mov_b32_e32 v40, v34
	v_mov_b32_e32 v41, v34
	v_mov_b32_e32 v42, v34
	v_mov_b32_e32 v43, v34
	v_mov_b32_e32 v44, v34
	v_mov_b32_e32 v45, v34
	v_mov_b32_e32 v46, v34
	v_mov_b32_e32 v47, v34
	v_mov_b32_e32 v48, v34
	v_mov_b32_e32 v49, v34
; #define MFMA(a, b, c) __builtin_amdgcn_mfma_f32_32x32x16_bf16((a), (b), (c), 0, 0, 0)
; template <int N> DI void lgkm_wait() { asm volatile("s_waitcnt lgkmcnt(%0)" :: "i"(N) : "memory"); }
; #define SBAR() __builtin_amdgcn_sched_barrier(0)
;   static DI void run(unsigned vaddr, s16x4 (&lo)[R], s16x4 (&hi)[R], const f32x16& p0, const f32x16& p1, bf16x8& pfc, f32x16 (&o)[4]) {
;     constexpr int issued = (J + R < NF) ? (J + R) : NF;
;     if constexpr ((J & 3) == 0) {
;       if constexpr ((J >> 2) == 0) pfc = pack8<0>(p0);
;       else if constexpr ((J >> 2) == 1) pfc = pack8<8>(p0);
;       else if constexpr ((J >> 2) == 2) pfc = pack8<0>(p1);
;       else pfc = pack8<8>(p1);
;     }
;     lgkm_wait<2 * (issued - J - 1)>(); SBAR();
;     o[J & 3] = MFMA(__builtin_shufflevector(lo[J % R], hi[J % R], 0, 1, 2, 3, 4, 5, 6, 7), pfc, o[J & 3]);
;     SBAR();
;     if (J + R < NF) {
;       constexpr int off = ((J + R) & 3) * 32 * 136 + ((J + R) >> 2) * 32;
;       lo[J % R] = lds_rd64<off>(vaddr); hi[J % R] = lds_rd64<off + 16>(vaddr); SBAR();
;     }
;     if constexpr (J + 1 < NF) PvStep<J + 1, NF, R>::run(vaddr, lo, hi, p0, p1, pfc, o);
;   }
; template <int DQK, int MODE, bool PIPE>
; DI void attn_core(const u16* __restrict__ Qg, const u16* __restrict__ Kg, const u16* __restrict__ Vtg, int ntiles,
;                   int kr_lo, int rs, int r_q, int c_q, int cs, const float* biasL, char* lds, f32x16 (&o)[4], float& l_out, int tid) {
;     ...
;     for (int i = 0; i < 16; ++i) { p0[i] = __builtin_amdgcn_exp2f(p0[i]); p1[i] = __builtin_amdgcn_exp2f(p1[i]); ps += p0[i] + p1[i]; }
;     l += ps;
;     const char* vb = lds + (t & 1) * A_BUF + A_VOFF + r32 * 136 + h * 8;
;     {
;       bf16x8 pfc;
;       constexpr int R = PV_RING;
;       const unsigned vaddr = (unsigned)(size_t)vb;
;       s16x4 vlo[R], vhi[R];
;       SBAR();
;       vlo[0] = lds_rd64<0>(vaddr); vhi[0] = lds_rd64<16>(vaddr);
;       vlo[1] = lds_rd64<32 * 136>(vaddr); vhi[1] = lds_rd64<32 * 136 + 16>(vaddr);
;       if (R > 2) { vlo[2 % R] = lds_rd64<64 * 136>(vaddr); vhi[2 % R] = lds_rd64<64 * 136 + 16>(vaddr); }
;       if (R > 3) { vlo[3 % R] = lds_rd64<96 * 136>(vaddr); vhi[3 % R] = lds_rd64<96 * 136 + 16>(vaddr); }
;       SBAR();
;       __builtin_amdgcn_s_setprio(1);
;       PvStep<0, 16, R>::run(vaddr, vlo, vhi, p0, p1, pfc, o);
;       __builtin_amdgcn_s_setprio(0);
.LBB0_860:
	v_add_u32_e32 v156, s12, v168
	v_add3_u32 v160, v156, v166, s33
	ds_read_b64 v[156:157], v160 offset:0
	ds_read_b64 v[158:159], v160 offset:16
	ds_read_b64 v[170:171], v160 offset:0x1100
	ds_read_b64 v[172:173], v160 offset:0x1110
	ds_read_b64 v[174:175], v160 offset:0x2200
	ds_read_b64 v[176:177], v160 offset:0x2210
	ds_read_b64 v[216:217], v160 offset:0x3300
	ds_read_b64 v[218:219], v160 offset:0x3310
	v_exp_f32_e32 v82, v82
	v_exp_f32_e32 v98, v98
	v_exp_f32_e32 v83, v83
	v_exp_f32_e32 v99, v99
	v_exp_f32_e32 v84, v84
	v_exp_f32_e32 v100, v100
	v_exp_f32_e32 v85, v85
	v_exp_f32_e32 v101, v101
	v_exp_f32_e32 v86, v86
	v_exp_f32_e32 v102, v102
	v_exp_f32_e32 v87, v87
	v_exp_f32_e32 v103, v103
	v_exp_f32_e32 v88, v88
	v_exp_f32_e32 v104, v104
	v_exp_f32_e32 v89, v89
	v_exp_f32_e32 v105, v105
	v_exp_f32_e32 v90, v90
	v_exp_f32_e32 v106, v106
	v_exp_f32_e32 v91, v91
	v_exp_f32_e32 v107, v107
	v_exp_f32_e32 v92, v92
	v_exp_f32_e32 v108, v108
	v_exp_f32_e32 v93, v93
	v_exp_f32_e32 v109, v109
	v_exp_f32_e32 v94, v94
	v_exp_f32_e32 v110, v110
	v_exp_f32_e32 v95, v95
	v_exp_f32_e32 v111, v111
	v_exp_f32_e32 v96, v96
	v_exp_f32_e32 v112, v112
	v_exp_f32_e32 v97, v97
	v_exp_f32_e32 v113, v113
	s_setprio 1
	s_waitcnt lgkmcnt(4)
	v_cvt_pk_bf16_f32 v220, v82, v83
	v_cvt_pk_bf16_f32 v221, v84, v85
	v_cvt_pk_bf16_f32 v222, v86, v87
	v_cvt_pk_bf16_f32 v223, v88, v89
	s_nop 1
	v_mfma_f32_32x32x16_bf16 v[66:81], v[156:159], v[220:223], v[66:81]
	ds_read_b64 v[156:157], v160 offset:32
	ds_read_b64 v[158:159], v160 offset:48
	v_mfma_f32_32x32x16_bf16 v[50:65], v[170:173], v[220:223], v[50:65]
	ds_read_b64 v[170:171], v160 offset:0x1120
	ds_read_b64 v[172:173], v160 offset:0x1130
	s_waitcnt lgkmcnt(4)
	v_mfma_f32_32x32x16_bf16 v[18:33], v[174:177], v[220:223], v[18:33]
	ds_read_b64 v[174:175], v160 offset:0x2220
	ds_read_b64 v[176:177], v160 offset:0x2230
	v_mfma_f32_32x32x16_bf16 v[2:17], v[216:219], v[220:223], v[2:17]
	ds_read_b64 v[216:217], v160 offset:0x3320
	ds_read_b64 v[218:219], v160 offset:0x3330
	s_waitcnt lgkmcnt(4)
	v_cvt_pk_bf16_f32 v220, v90, v91
	v_cvt_pk_bf16_f32 v221, v92, v93
	v_cvt_pk_bf16_f32 v222, v94, v95
	v_cvt_pk_bf16_f32 v223, v96, v97
	s_nop 1
	v_mfma_f32_32x32x16_bf16 v[66:81], v[156:159], v[220:223], v[66:81]
	ds_read_b64 v[156:157], v160 offset:64
	ds_read_b64 v[158:159], v160 offset:0x50
	v_mfma_f32_32x32x16_bf16 v[50:65], v[170:173], v[220:223], v[50:65]
	ds_read_b64 v[170:171], v160 offset:0x1140
	ds_read_b64 v[172:173], v160 offset:0x1150
	s_waitcnt lgkmcnt(4)
	v_mfma_f32_32x32x16_bf16 v[18:33], v[174:177], v[220:223], v[18:33]
	ds_read_b64 v[174:175], v160 offset:0x2240
	ds_read_b64 v[176:177], v160 offset:0x2250
	v_mfma_f32_32x32x16_bf16 v[2:17], v[216:219], v[220:223], v[2:17]
	ds_read_b64 v[216:217], v160 offset:0x3340
	ds_read_b64 v[218:219], v160 offset:0x3350
	s_waitcnt lgkmcnt(4)
	v_cvt_pk_bf16_f32 v220, v98, v99
	v_cvt_pk_bf16_f32 v221, v100, v101
	v_cvt_pk_bf16_f32 v222, v102, v103
	v_cvt_pk_bf16_f32 v223, v104, v105
	s_nop 1
	v_mfma_f32_32x32x16_bf16 v[66:81], v[156:159], v[220:223], v[66:81]
	ds_read_b64 v[156:157], v160 offset:0x60
	ds_read_b64 v[158:159], v160 offset:0x70
	v_mfma_f32_32x32x16_bf16 v[50:65], v[170:173], v[220:223], v[50:65]
	ds_read_b64 v[170:171], v160 offset:0x1160
	ds_read_b64 v[172:173], v160 offset:0x1170
	s_waitcnt lgkmcnt(4)
	v_mfma_f32_32x32x16_bf16 v[18:33], v[174:177], v[220:223], v[18:33]
	ds_read_b64 v[174:175], v160 offset:0x2260
	ds_read_b64 v[176:177], v160 offset:0x2270
	v_mfma_f32_32x32x16_bf16 v[2:17], v[216:219], v[220:223], v[2:17]
	ds_read_b64 v[216:217], v160 offset:0x3360
	ds_read_b64 v[218:219], v160 offset:0x3370
	s_waitcnt lgkmcnt(4)
	v_cvt_pk_bf16_f32 v220, v106, v107
	v_cvt_pk_bf16_f32 v221, v108, v109
	v_cvt_pk_bf16_f32 v222, v110, v111
	v_cvt_pk_bf16_f32 v223, v112, v113
	s_nop 1
	v_mfma_f32_32x32x16_bf16 v[66:81], v[156:159], v[220:223], v[66:81]
	v_mfma_f32_32x32x16_bf16 v[50:65], v[170:173], v[220:223], v[50:65]
	s_waitcnt lgkmcnt(0)
	v_mfma_f32_32x32x16_bf16 v[18:33], v[174:177], v[220:223], v[18:33]
	v_mfma_f32_32x32x16_bf16 v[2:17], v[216:219], v[220:223], v[2:17]
	s_setprio 0
	s_andn2_b64 vcc, exec, s[0:1]
	s_cbranch_vccnz .LBB0_862
	s_bitcmp1_b32 s11, 0
	s_cselect_b32 s0, 0xa800, 0
	v_add_u32_e32 v156, s0, v143
	s_waitcnt vmcnt(0)
	ds_write_b128 v156, v[138:141]

; #define LAS __attribute__((address_space(3)))
; __global__ __launch_bounds__(NT_) void k_mega(Params p) {
;   extern __shared__ __attribute__((aligned(16))) char lds[];
;   cg::grid_group grid = cg::this_grid();
;   volatile LAS unsigned* st = (volatile LAS unsigned*)(lds + XB_LDS_OFF);
;   if (threadIdx.x == 0) { st[0] = 0u; st[1] = 0u; }
;   __syncthreads();
;   const XcdBarrier xb = xcd_barrier_post(p.xbar, st);
;   phase0a(p, lds);
;   grid.sync();
;   row_phase(p, -1);
;   xcd_barrier(xb);
;   for (int layer = 0; layer < DEPTH; ++layer) {
;     phase_gemm_in(p, layer, lds);
;     xcd_barrier(xb);
;     phase_gemm_up(p, layer, lds);
;     xcd_barrier(xb);
;     phase_attn(p, layer, lds);
;     xcd_barrier(xb);
;     phase_gemm_out(p, layer, lds);
;     xcd_barrier(xb);
;     row_phase(p, layer);
;     if (layer + 1 < DEPTH) xcd_barrier(xb);
;   }
; }
	.amdhsa_kernel _Z6k_mega6Params
		.amdhsa_group_segment_fixed_size 0
		.amdhsa_private_segment_fixed_size 0
		.amdhsa_kernarg_size 632
		.amdhsa_user_sgpr_count 2
		.amdhsa_user_sgpr_dispatch_ptr 0
		.amdhsa_user_sgpr_queue_ptr 0
		.amdhsa_user_sgpr_kernarg_segment_ptr 1
		.amdhsa_user_sgpr_dispatch_id 0
		.amdhsa_user_sgpr_kernarg_preload_length 0
		.amdhsa_user_sgpr_kernarg_preload_offset 0
		.amdhsa_user_sgpr_private_segment_size 0
		.amdhsa_uses_dynamic_stack 0
		.amdhsa_enable_private_segment 0
		.amdhsa_system_sgpr_workgroup_id_x 1
		.amdhsa_system_sgpr_workgroup_id_y 0
		.amdhsa_system_sgpr_workgroup_id_z 0
		.amdhsa_system_sgpr_workgroup_info 0
		.amdhsa_system_vgpr_workitem_id 2
		.amdhsa_next_free_vgpr 256
		.amdhsa_next_free_sgpr 102
		.amdhsa_accum_offset 256
		.amdhsa_reserve_vcc 1
		.amdhsa_float_round_mode_32 0
		.amdhsa_float_round_mode_16_64 0
		.amdhsa_float_denorm_mode_32 3
		.amdhsa_float_denorm_mode_16_64 3
		.amdhsa_dx10_clamp 1
		.amdhsa_ieee_mode 1
		.amdhsa_fp16_overflow 0
		.amdhsa_tg_split 0
		.amdhsa_exception_fp_ieee_invalid_op 0
		.amdhsa_exception_fp_denorm_src 0
		.amdhsa_exception_fp_ieee_div_zero 0
		.amdhsa_exception_fp_ieee_overflow 0
		.amdhsa_exception_fp_ieee_underflow 0
		.amdhsa_exception_fp_ieee_inexact 0
		.amdhsa_exception_int_div_zero 0
	.end_amdhsa_kernel

; #define LAS __attribute__((address_space(3)))
; __global__ __launch_bounds__(NT_) void k_mega(Params p) {
;   extern __shared__ __attribute__((aligned(16))) char lds[];
;   cg::grid_group grid = cg::this_grid();
;   volatile LAS unsigned* st = (volatile LAS unsigned*)(lds + XB_LDS_OFF);
;   if (threadIdx.x == 0) { st[0] = 0u; st[1] = 0u; }
;   __syncthreads();
;   const XcdBarrier xb = xcd_barrier_post(p.xbar, st);
;   phase0a(p, lds);
;   grid.sync();
;   row_phase(p, -1);
;   xcd_barrier(xb);
;   for (int layer = 0; layer < DEPTH; ++layer) {
;     phase_gemm_in(p, layer, lds);
;     xcd_barrier(xb);
;     phase_gemm_up(p, layer, lds);
;     xcd_barrier(xb);
;     phase_attn(p, layer, lds);
;     xcd_barrier(xb);
;     phase_gemm_out(p, layer, lds);
;     xcd_barrier(xb);
;     row_phase(p, layer);
;     if (layer + 1 < DEPTH) xcd_barrier(xb);
;   }
; }
amdhsa.kernels:
  - .agpr_count:     0
    .args:
      - .offset:         0
        .size:           376
        .value_kind:     by_value
      - .offset:         376
        .size:           4
        .value_kind:     hidden_block_count_x
      - .offset:         380
        .size:           4
        .value_kind:     hidden_block_count_y
      - .offset:         384
        .size:           4
        .value_kind:     hidden_block_count_z
      - .offset:         388
        .size:           2
        .value_kind:     hidden_group_size_x
      - .offset:         390
        .size:           2
        .value_kind:     hidden_group_size_y
      - .offset:         392
        .size:           2
        .value_kind:     hidden_group_size_z
      - .offset:         394
        .size:           2
        .value_kind:     hidden_remainder_x
      - .offset:         396
        .size:           2
        .value_kind:     hidden_remainder_y
      - .offset:         398
        .size:           2
        .value_kind:     hidden_remainder_z
      - .offset:         416
        .size:           8
        .value_kind:     hidden_global_offset_x
      - .offset:         424
        .size:           8
        .value_kind:     hidden_global_offset_y
      - .offset:         432
        .size:           8
        .value_kind:     hidden_global_offset_z
      - .offset:         440
        .size:           2
        .value_kind:     hidden_grid_dims
      - .offset:         464
        .size:           8
        .value_kind:     hidden_multigrid_sync_arg
      - .offset:         496
        .size:           4
        .value_kind:     hidden_dynamic_lds_size
    .group_segment_fixed_size: 0
    .kernarg_segment_align: 8
    .kernarg_segment_size: 632
    .language:       OpenCL C
    .language_version:
      - 2
      - 0
    .max_flat_workgroup_size: 512
    .name:           _Z6k_mega6Params
    .private_segment_fixed_size: 0
    .sgpr_count:     108
    .sgpr_spill_count: 251
    .symbol:         _Z6k_mega6Params.kd
    .uniform_work_group_size: 1
    .uses_dynamic_stack: false
    .vgpr_count:     256
    .vgpr_spill_count: 0
    .wavefront_size: 64
